# s28 + G1b: leading half's alignment barrier moved from before to after its epilogue (its epilogue overlaps the trailing half's last MMA; epilogues run one after the other)
# speedup vs baseline: 1.0025x; 1.0025x over previous
; #define PG8_STAGE(bufoff, gbase, voff) do { _Pragma("unroll") for (int _i = 0; _i < 2; ++_i) \
;         __builtin_amdgcn_global_load_lds((const unsigned*)((const char*)(gbase) + (voff)[_i]), (PG8_LAS unsigned*)(lds + (bufoff) + ldsw + _i * 8192), 16, 0, 0); } while (0)
; #define PG8_LDA(dst, b, h) do { _Pragma("unroll") for (int m = 0; m < 4; ++m) _Pragma("unroll") for (int k = 0; k < 2; ++k) dst[m][k] = *(const PG8_LAS bf16x8*)(lds + PG8_SA(b, h) + aoff + m * 2048 + k * 1024); } while (0)
; #define PG8_LDB(dst, b, h) do { _Pragma("unroll") for (int n = 0; n < 2; ++n) _Pragma("unroll") for (int k = 0; k < 2; ++k) dst[n][k] = *(const PG8_LAS bf16x8*)(lds + PG8_SB(b, h) + boff + n * 2048 + k * 1024); } while (0)
; #define PG8_MMA(ai, bj, At, Bt) do { __builtin_amdgcn_s_setprio(1); _Pragma("unroll") for (int m = 0; m < 4; ++m) _Pragma("unroll") for (int n = 0; n < 2; ++n) _Pragma("unroll") for (int k = 0; k < 2; ++k) \
;         mma1<I8>(acc[ai][bj][m][n], Bt[n][k], At[m][k]); __builtin_amdgcn_s_setprio(0); } while (0)
; #define PG8_WAIT_V(n) asm volatile("s_waitcnt vmcnt(" #n ")" ::: "memory")
; #define PG8_WAIT_L(n) asm volatile("s_waitcnt lgkmcnt(" #n ")" ::: "memory")
; #define PG8_BAR __builtin_amdgcn_s_barrier()
; #define PG8_SCHED __builtin_amdgcn_sched_barrier(0)
; template <class Epi, class Sched, bool ALIGN_EPI = false, bool SP2 = false, bool I8 = false>
; __device__ __forceinline__ void gemm_phase(PG8_LAS unsigned char* lds, const Gemm g, const Sched& S, const Epi& E, const int tid) {
;     ...
;             const char* a1 = cA + (size_t)(t + 1) * kstep;
;             const char* a2 = last ? nA : cA + (size_t)(t + 2) * kstep; const char* b2 = last ? nB : cB + (size_t)(t + 2) * kstep;
;             const char* a3 = a2 + kstep; const char* b3 = b2 + kstep;
;             if (last && has_next) S.a_ready(nxt);
;             if constexpr (SP2) {
;             PG8_LDB(B0, 0, 0); PG8_LDB(B1, 0, 1); PG8_SCHED; PG8_LDA(At, 0, 0); PG8_STAGE(PG8_SA(1, 1), a1 + hstepA, voffA);
;             PG8_WAIT_V(8); PG8_WAIT_L(0); PG8_BAR; PG8_MMA(0, 0, At, B0); PG8_MMA(0, 1, At, B1); PG8_BAR; PG8_SCHED;
;             PG8_LDA(At, 0, 1); PG8_STAGE(PG8_SB(0, 0), b2, voffB); PG8_STAGE(PG8_SB(0, 1), b2 + hstepB, voffB); PG8_STAGE(PG8_SA(0, 0), a2, voffA);
;             PG8_WAIT_V(8); PG8_WAIT_L(0); PG8_BAR; PG8_MMA(1, 0, At, B0); PG8_MMA(1, 1, At, B1); PG8_BAR; PG8_SCHED;
.LBB0_335:
	s_add_u32 s54, s46, 0xfff80080
	s_addc_u32 s55, s47, -1
	s_add_i32 s70, 0, 0x10000
	s_cmp_eq_u32 s65, 28
	s_cselect_b32 s57, s5, s55
	s_cselect_b32 s56, s31, s54
	s_cselect_b32 s55, s13, s60
	s_cselect_b32 s54, s41, s49
	s_add_i32 s87, 0, 0x14000
	v_add_u32_e32 v68, s70, v187
	v_add_u32_e32 v168, s87, v187
	ds_read_b128 v[48:51], v68
	ds_read_b128 v[52:55], v68 offset:1024
	ds_read_b128 v[64:67], v68 offset:2048
	ds_read_b128 v[68:71], v68 offset:3072
	ds_read_b128 v[156:159], v168
	ds_read_b128 v[160:163], v168 offset:1024
	ds_read_b128 v[164:167], v168 offset:2048
	ds_read_b128 v[168:171], v168 offset:3072
	v_lshl_add_u64 v[184:185], s[46:47], 0, v[154:155]
	s_add_i32 m0, s80, 0xc000
	ds_read_b128 v[172:175], v189
	ds_read_b128 v[176:179], v189 offset:1024
	ds_read_b128 v[180:183], v189 offset:2048
	ds_read_b128 v[190:193], v189 offset:3072
	ds_read_b128 v[200:203], v189 offset:4096
	ds_read_b128 v[204:207], v189 offset:5120
	ds_read_b128 v[208:211], v189 offset:6144
	ds_read_b128 v[212:215], v189 offset:7168
	global_load_lds_dwordx4 v[184:185], off
	v_lshl_add_u64 v[184:185], s[46:47], 0, v[152:153]
	s_add_i32 m0, s80, 0xe000
	s_nop 0
	global_load_lds_dwordx4 v[184:185], off
	s_waitcnt vmcnt(8)
	s_waitcnt lgkmcnt(0)
	s_barrier
	s_setprio 1
	s_waitcnt lgkmcnt(0)
	v_mfma_i32_16x16x64_i8 v[142:145], v[48:51], v[172:175], v[142:145]
	v_mfma_i32_16x16x64_i8 v[138:141], v[64:67], v[172:175], v[138:141]
	v_mfma_i32_16x16x64_i8 v[126:129], v[48:51], v[180:183], v[126:129]
	v_mfma_i32_16x16x64_i8 v[122:125], v[64:67], v[180:183], v[122:125]
	v_mfma_i32_16x16x64_i8 v[110:113], v[48:51], v[200:203], v[110:113]
	v_mfma_i32_16x16x64_i8 v[106:109], v[64:67], v[200:203], v[106:109]
	v_mfma_i32_16x16x64_i8 v[92:95], v[48:51], v[208:211], v[92:95]
	v_mfma_i32_16x16x64_i8 v[88:91], v[64:67], v[208:211], v[88:91]
	v_mfma_i32_16x16x64_i8 v[142:145], v[52:55], v[176:179], v[142:145]
	v_mfma_i32_16x16x64_i8 v[138:141], v[68:71], v[176:179], v[138:141]
	v_mfma_i32_16x16x64_i8 v[126:129], v[52:55], v[190:193], v[126:129]
	v_mfma_i32_16x16x64_i8 v[122:125], v[68:71], v[190:193], v[122:125]
	v_mfma_i32_16x16x64_i8 v[110:113], v[52:55], v[204:207], v[110:113]
	v_mfma_i32_16x16x64_i8 v[106:109], v[68:71], v[204:207], v[106:109]
	v_mfma_i32_16x16x64_i8 v[92:95], v[52:55], v[212:215], v[92:95]
	v_mfma_i32_16x16x64_i8 v[88:91], v[68:71], v[212:215], v[88:91]
	s_setprio 0
	s_setprio 1
	v_mfma_i32_16x16x64_i8 v[134:137], v[156:159], v[172:175], v[134:137]
	v_mfma_i32_16x16x64_i8 v[130:133], v[164:167], v[172:175], v[130:133]
	v_mfma_i32_16x16x64_i8 v[118:121], v[156:159], v[180:183], v[118:121]
	v_mfma_i32_16x16x64_i8 v[114:117], v[164:167], v[180:183], v[114:117]
	v_mfma_i32_16x16x64_i8 v[102:105], v[156:159], v[200:203], v[102:105]
	v_mfma_i32_16x16x64_i8 v[98:101], v[164:167], v[200:203], v[98:101]
	v_mfma_i32_16x16x64_i8 v[84:87], v[156:159], v[208:211], v[84:87]
	v_mfma_i32_16x16x64_i8 v[80:83], v[164:167], v[208:211], v[80:83]
	v_mfma_i32_16x16x64_i8 v[134:137], v[160:163], v[176:179], v[134:137]
	v_mfma_i32_16x16x64_i8 v[130:133], v[168:171], v[176:179], v[130:133]
	v_mfma_i32_16x16x64_i8 v[118:121], v[160:163], v[190:193], v[118:121]
	v_mfma_i32_16x16x64_i8 v[114:117], v[168:171], v[190:193], v[114:117]
	v_mfma_i32_16x16x64_i8 v[102:105], v[160:163], v[204:207], v[102:105]
	v_mfma_i32_16x16x64_i8 v[98:101], v[168:171], v[204:207], v[98:101]
	v_mfma_i32_16x16x64_i8 v[84:87], v[160:163], v[212:215], v[84:87]
	v_mfma_i32_16x16x64_i8 v[80:83], v[168:171], v[212:215], v[80:83]
	s_setprio 0
	s_barrier
	s_add_i32 s70, s70, s75
	v_lshl_add_u64 v[184:185], s[54:55], 0, v[96:97]
	s_mov_b32 m0, s70
	ds_read_b128 v[172:175], v189 offset:16384
	ds_read_b128 v[176:179], v189 offset:17408
	ds_read_b128 v[180:183], v189 offset:18432
	ds_read_b128 v[190:193], v189 offset:19456
	ds_read_b128 v[200:203], v189 offset:20480
	ds_read_b128 v[204:207], v189 offset:21504
	ds_read_b128 v[208:211], v189 offset:22528
	ds_read_b128 v[212:215], v189 offset:23552
	global_load_lds_dwordx4 v[184:185], off
	s_add_i32 m0, s70, 0x2000
	s_add_u32 s76, s54, 0x80000
	v_lshl_add_u64 v[194:195], s[54:55], 0, v[150:151]
	s_addc_u32 s77, s55, 0
	s_add_i32 s70, s87, s75
	global_load_lds_dwordx4 v[194:195], off
	v_lshl_add_u64 v[216:217], s[76:77], 0, v[96:97]
	s_mov_b32 m0, s70
	v_lshl_add_u64 v[218:219], s[56:57], 0, v[148:149]
	global_load_lds_dwordx4 v[216:217], off
	v_lshl_add_u64 v[216:217], s[76:77], 0, v[150:151]
	s_add_i32 m0, s70, 0x2000
	s_nop 0
	global_load_lds_dwordx4 v[216:217], off
	v_lshl_add_u64 v[216:217], s[56:57], 0, v[146:147]
	s_mov_b32 m0, s80
	s_nop 0
	global_load_lds_dwordx4 v[216:217], off
	s_mov_b32 m0, s85
	s_nop 0
	global_load_lds_dwordx4 v[218:219], off
	s_waitcnt vmcnt(8)
	s_waitcnt lgkmcnt(0)
	s_barrier
; #define PG8_STAGE(bufoff, gbase, voff) do { _Pragma("unroll") for (int _i = 0; _i < 2; ++_i) \
;         __builtin_amdgcn_global_load_lds((const unsigned*)((const char*)(gbase) + (voff)[_i]), (PG8_LAS unsigned*)(lds + (bufoff) + ldsw + _i * 8192), 16, 0, 0); } while (0)
; #define PG8_LDA(dst, b, h) do { _Pragma("unroll") for (int m = 0; m < 4; ++m) _Pragma("unroll") for (int k = 0; k < 2; ++k) dst[m][k] = *(const PG8_LAS bf16x8*)(lds + PG8_SA(b, h) + aoff + m * 2048 + k * 1024); } while (0)
; #define PG8_LDB(dst, b, h) do { _Pragma("unroll") for (int n = 0; n < 2; ++n) _Pragma("unroll") for (int k = 0; k < 2; ++k) dst[n][k] = *(const PG8_LAS bf16x8*)(lds + PG8_SB(b, h) + boff + n * 2048 + k * 1024); } while (0)
; #define PG8_MMA(ai, bj, At, Bt) do { __builtin_amdgcn_s_setprio(1); _Pragma("unroll") for (int m = 0; m < 4; ++m) _Pragma("unroll") for (int n = 0; n < 2; ++n) _Pragma("unroll") for (int k = 0; k < 2; ++k) \
;         mma1<I8>(acc[ai][bj][m][n], Bt[n][k], At[m][k]); __builtin_amdgcn_s_setprio(0); } while (0)
; #define PG8_WAIT_V(n) asm volatile("s_waitcnt vmcnt(" #n ")" ::: "memory")
; #define PG8_WAIT_L(n) asm volatile("s_waitcnt lgkmcnt(" #n ")" ::: "memory")
; #define PG8_BAR __builtin_amdgcn_s_barrier()
; #define PG8_SCHED __builtin_amdgcn_sched_barrier(0)
; template <class Epi, class Sched, bool ALIGN_EPI = false, bool SP2 = false, bool I8 = false>
; __device__ __forceinline__ void gemm_phase(PG8_LAS unsigned char* lds, const Gemm g, const Sched& S, const Epi& E, const int tid) {
;     ...
;             PG8_WAIT_V(8); PG8_WAIT_L(0); PG8_BAR; PG8_MMA(1, 0, At, B0); PG8_MMA(1, 1, At, B1); PG8_BAR; PG8_SCHED;
;             PG8_LDB(B0, 1, 0); PG8_LDB(B1, 1, 1); PG8_SCHED; PG8_LDA(At, 1, 0); PG8_STAGE(PG8_SA(0, 1), a2 + hstepA, voffA);
;             PG8_WAIT_V(8); PG8_WAIT_L(0); PG8_BAR; PG8_MMA(0, 0, At, B0); PG8_MMA(0, 1, At, B1); PG8_BAR; PG8_SCHED;
	s_setprio 1
	s_waitcnt lgkmcnt(0)
	v_mfma_i32_16x16x64_i8 v[76:79], v[48:51], v[172:175], v[76:79]
	v_mfma_i32_16x16x64_i8 v[72:75], v[64:67], v[172:175], v[72:75]
	v_mfma_i32_16x16x64_i8 v[44:47], v[48:51], v[180:183], v[44:47]
	v_mfma_i32_16x16x64_i8 v[40:43], v[64:67], v[180:183], v[40:43]
	v_mfma_i32_16x16x64_i8 v[28:31], v[48:51], v[200:203], v[28:31]
	v_mfma_i32_16x16x64_i8 v[24:27], v[64:67], v[200:203], v[24:27]
	v_mfma_i32_16x16x64_i8 v[12:15], v[48:51], v[208:211], v[12:15]
	v_mfma_i32_16x16x64_i8 v[8:11], v[64:67], v[208:211], v[8:11]
	v_mfma_i32_16x16x64_i8 v[76:79], v[52:55], v[176:179], v[76:79]
	v_mfma_i32_16x16x64_i8 v[72:75], v[68:71], v[176:179], v[72:75]
	v_mfma_i32_16x16x64_i8 v[44:47], v[52:55], v[190:193], v[44:47]
	v_mfma_i32_16x16x64_i8 v[40:43], v[68:71], v[190:193], v[40:43]
	v_mfma_i32_16x16x64_i8 v[28:31], v[52:55], v[204:207], v[28:31]
	v_mfma_i32_16x16x64_i8 v[24:27], v[68:71], v[204:207], v[24:27]
	v_mfma_i32_16x16x64_i8 v[12:15], v[52:55], v[212:215], v[12:15]
	v_mfma_i32_16x16x64_i8 v[8:11], v[68:71], v[212:215], v[8:11]
	s_setprio 0
	s_setprio 1
	v_mfma_i32_16x16x64_i8 v[36:39], v[156:159], v[180:183], v[36:39]
	v_mfma_i32_16x16x64_i8 v[32:35], v[164:167], v[180:183], v[32:35]
	v_mfma_i32_16x16x64_i8 v[20:23], v[156:159], v[200:203], v[20:23]
	v_mfma_i32_16x16x64_i8 v[16:19], v[164:167], v[200:203], v[16:19]
	v_mfma_i32_16x16x64_i8 v[4:7], v[156:159], v[208:211], v[4:7]
	v_mfma_i32_16x16x64_i8 v[0:3], v[164:167], v[208:211], v[0:3]
	v_mfma_i32_16x16x64_i8 v[48:51], v[156:159], v[172:175], v[60:63]
	v_mfma_i32_16x16x64_i8 v[52:55], v[164:167], v[172:175], v[56:59]
	v_mfma_i32_16x16x64_i8 v[36:39], v[160:163], v[190:193], v[36:39]
	v_mfma_i32_16x16x64_i8 v[32:35], v[168:171], v[190:193], v[32:35]
	v_mfma_i32_16x16x64_i8 v[20:23], v[160:163], v[204:207], v[20:23]
	v_mfma_i32_16x16x64_i8 v[16:19], v[168:171], v[204:207], v[16:19]
	v_mfma_i32_16x16x64_i8 v[4:7], v[160:163], v[212:215], v[4:7]
	v_mfma_i32_16x16x64_i8 v[0:3], v[168:171], v[212:215], v[0:3]
	v_mfma_i32_16x16x64_i8 v[48:51], v[160:163], v[176:179], v[48:51]
	v_mfma_i32_16x16x64_i8 v[52:55], v[168:171], v[176:179], v[52:55]
	s_setprio 0
	s_barrier
	s_add_i32 s70, 0, 0x18000
	s_add_i32 s76, 0, 0x1c000
	v_add_u32_e32 v68, s70, v187
	v_add_u32_e32 v168, s76, v187
	ds_read_b128 v[56:59], v68
	ds_read_b128 v[60:63], v68 offset:1024
	ds_read_b128 v[64:67], v68 offset:2048
	ds_read_b128 v[68:71], v68 offset:3072
	ds_read_b128 v[156:159], v168
	ds_read_b128 v[160:163], v168 offset:1024
	ds_read_b128 v[164:167], v168 offset:2048
	ds_read_b128 v[168:171], v168 offset:3072
	s_add_u32 s56, s56, 0x80000
	s_addc_u32 s57, s57, 0
	s_mov_b32 m0, s86
	v_lshl_add_u64 v[220:221], s[56:57], 0, v[146:147]
	ds_read_b128 v[172:175], v189 offset:32768
	ds_read_b128 v[176:179], v189 offset:33792
	ds_read_b128 v[180:183], v189 offset:34816
	ds_read_b128 v[190:193], v189 offset:35840
	ds_read_b128 v[200:203], v189 offset:36864
	ds_read_b128 v[204:207], v189 offset:37888
	ds_read_b128 v[208:211], v189 offset:38912
	ds_read_b128 v[212:215], v189 offset:39936
	global_load_lds_dwordx4 v[220:221], off
	v_lshl_add_u64 v[220:221], s[56:57], 0, v[148:149]
	s_mov_b32 m0, s88
	s_nop 0
	global_load_lds_dwordx4 v[220:221], off
	s_waitcnt vmcnt(8)
	s_waitcnt lgkmcnt(0)
	s_barrier
	s_setprio 1
	s_waitcnt lgkmcnt(0)
	v_mfma_i32_16x16x64_i8 v[142:145], v[56:59], v[172:175], v[142:145]
	v_mfma_i32_16x16x64_i8 v[138:141], v[64:67], v[172:175], v[138:141]
	v_mfma_i32_16x16x64_i8 v[126:129], v[56:59], v[180:183], v[126:129]
	v_mfma_i32_16x16x64_i8 v[122:125], v[64:67], v[180:183], v[122:125]
	v_mfma_i32_16x16x64_i8 v[110:113], v[56:59], v[200:203], v[110:113]
	v_mfma_i32_16x16x64_i8 v[106:109], v[64:67], v[200:203], v[106:109]
	v_mfma_i32_16x16x64_i8 v[92:95], v[56:59], v[208:211], v[92:95]
	v_mfma_i32_16x16x64_i8 v[88:91], v[64:67], v[208:211], v[88:91]
	v_mfma_i32_16x16x64_i8 v[142:145], v[60:63], v[176:179], v[142:145]
	v_mfma_i32_16x16x64_i8 v[138:141], v[68:71], v[176:179], v[138:141]
	v_mfma_i32_16x16x64_i8 v[126:129], v[60:63], v[190:193], v[126:129]
	v_mfma_i32_16x16x64_i8 v[122:125], v[68:71], v[190:193], v[122:125]
	v_mfma_i32_16x16x64_i8 v[110:113], v[60:63], v[204:207], v[110:113]
	v_mfma_i32_16x16x64_i8 v[106:109], v[68:71], v[204:207], v[106:109]
	v_mfma_i32_16x16x64_i8 v[92:95], v[60:63], v[212:215], v[92:95]
	v_mfma_i32_16x16x64_i8 v[88:91], v[68:71], v[212:215], v[88:91]
	s_setprio 0
	s_setprio 1
	v_mfma_i32_16x16x64_i8 v[134:137], v[156:159], v[172:175], v[134:137]
	v_mfma_i32_16x16x64_i8 v[130:133], v[164:167], v[172:175], v[130:133]
	v_mfma_i32_16x16x64_i8 v[118:121], v[156:159], v[180:183], v[118:121]
	v_mfma_i32_16x16x64_i8 v[114:117], v[164:167], v[180:183], v[114:117]
	v_mfma_i32_16x16x64_i8 v[102:105], v[156:159], v[200:203], v[102:105]
	v_mfma_i32_16x16x64_i8 v[98:101], v[164:167], v[200:203], v[98:101]
	v_mfma_i32_16x16x64_i8 v[84:87], v[156:159], v[208:211], v[84:87]
	v_mfma_i32_16x16x64_i8 v[80:83], v[164:167], v[208:211], v[80:83]
	v_mfma_i32_16x16x64_i8 v[134:137], v[160:163], v[176:179], v[134:137]
	v_mfma_i32_16x16x64_i8 v[130:133], v[168:171], v[176:179], v[130:133]
	v_mfma_i32_16x16x64_i8 v[118:121], v[160:163], v[190:193], v[118:121]
	v_mfma_i32_16x16x64_i8 v[114:117], v[168:171], v[190:193], v[114:117]
	v_mfma_i32_16x16x64_i8 v[102:105], v[160:163], v[204:207], v[102:105]
	v_mfma_i32_16x16x64_i8 v[98:101], v[168:171], v[204:207], v[98:101]
	v_mfma_i32_16x16x64_i8 v[84:87], v[160:163], v[212:215], v[84:87]
	v_mfma_i32_16x16x64_i8 v[80:83], v[168:171], v[212:215], v[80:83]
	s_setprio 0
	s_barrier
;     __device__ __forceinline__ void operator()(const i32x4 (&acc)[2][2][4][2], const Unit& u, int wr, int wc, int fr, int fq) const {
;     ...
;             for (int m = 0; m < 4; ++m) { const int row = row0 + ai * HALF + m * 16; const float rs = rs8[ai][m]; bf16_t* rowp = O + (size_t)row * ldc + col0;
; #pragma unroll
;                 for (int bj = 0; bj < 2; ++bj) { f32x4 v0, v1;
; template <class Epi, class Sched, bool ALIGN_EPI = false, bool SP2 = false, bool I8 = false>
; __device__ __forceinline__ void gemm_phase(PG8_LAS unsigned char* lds, const Gemm g, const Sched& S, const Epi& E, const int tid) {
;     ...
;             PG8_LDA(At, 1, 1); PG8_STAGE(PG8_SB(1, 0), b3, voffB); PG8_STAGE(PG8_SB(1, 1), b3 + hstepB, voffB); PG8_STAGE(PG8_SA(1, 0), a3, voffA);
;             PG8_WAIT_V(8); PG8_WAIT_L(0); PG8_BAR; PG8_MMA(1, 0, At, B0); PG8_MMA(1, 1, At, B1); PG8_BAR; PG8_SCHED;
;             if constexpr (HasMid<Epi>::value) { if (t + 2 == Epi::SEAM0 || t + 2 == Epi::SEAM1) E.mid(acc, cur, t + 2 == Epi::SEAM0 ? 0 : 1, wr, wc, fr, fq); }
;             } else {
;             PG8_LDB(B0, 0, 0); PG8_SCHED; PG8_LDA(At, 0, 0); PG8_STAGE(PG8_SA(1, 1), a1 + hstepA, voffA);
;             PG8_WAIT_L(8); PG8_BAR; PG8_WAIT_L(0); PG8_MMA(0, 0, At, B0); PG8_BAR; PG8_SCHED;
;             PG8_LDB(B1, 0, 1); PG8_STAGE(PG8_SB(0, 0), b2, voffB);
;             PG8_BAR; PG8_WAIT_L(0); PG8_MMA(0, 1, At, B1); PG8_BAR;
;             PG8_LDA(At, 0, 1); PG8_STAGE(PG8_SA(0, 0), a2, voffA);
;             PG8_BAR; PG8_WAIT_L(0); PG8_MMA(1, 0, At, B0); PG8_BAR; PG8_SCHED;
;             PG8_STAGE(PG8_SB(0, 1), b2 + hstepB, voffB);
;             PG8_WAIT_V(6); PG8_BAR; PG8_MMA(1, 1, At, B1); PG8_BAR;
;             PG8_LDB(B0, 1, 0); PG8_SCHED; PG8_LDA(At, 1, 0); PG8_STAGE(PG8_SA(0, 1), a2 + hstepA, voffA);
;             PG8_WAIT_L(8); PG8_BAR; PG8_WAIT_L(0); PG8_MMA(0, 0, At, B0); PG8_BAR; PG8_SCHED;
;             PG8_LDB(B1, 1, 1); PG8_STAGE(PG8_SB(1, 0), b3, voffB);
;             PG8_BAR; PG8_WAIT_L(0); PG8_MMA(0, 1, At, B1); PG8_BAR;
;             PG8_LDA(At, 1, 1); PG8_STAGE(PG8_SA(1, 0), a3, voffA);
;             PG8_BAR; PG8_WAIT_L(0); PG8_MMA(1, 0, At, B0); PG8_BAR; PG8_SCHED;
;             PG8_STAGE(PG8_SB(1, 1), b3 + hstepB, voffB);
;             PG8_WAIT_V(6); PG8_BAR; PG8_MMA(1, 1, At, B1); PG8_BAR;
;             }
;         }
;         if constexpr (ALIGN_EPI) { if (wr == 0) PG8_BAR; }
	s_add_i32 s56, s70, s75
	v_lshl_add_u64 v[184:185], v[184:185], 0, s[42:43]
	s_mov_b32 m0, s56
	ds_read_b128 v[172:175], v189 offset:49152
	ds_read_b128 v[176:179], v189 offset:50176
	ds_read_b128 v[180:183], v189 offset:51200
	ds_read_b128 v[190:193], v189 offset:52224
	ds_read_b128 v[200:203], v189 offset:53248
	ds_read_b128 v[204:207], v189 offset:54272
	ds_read_b128 v[208:211], v189 offset:55296
	ds_read_b128 v[212:215], v189 offset:56320
	global_load_lds_dwordx4 v[184:185], off
	s_add_i32 m0, s56, 0x2000
	s_add_u32 s54, s54, 0x80080
	v_lshl_add_u64 v[184:185], v[194:195], 0, s[42:43]
	s_addc_u32 s55, s55, 0
	s_add_i32 s56, s76, s75
	global_load_lds_dwordx4 v[184:185], off
	v_lshl_add_u64 v[184:185], s[54:55], 0, v[96:97]
	s_mov_b32 m0, s56
	s_nop 0
	global_load_lds_dwordx4 v[184:185], off
	v_lshl_add_u64 v[184:185], s[54:55], 0, v[150:151]
	s_add_i32 m0, s56, 0x2000
	s_nop 0
	global_load_lds_dwordx4 v[184:185], off
	v_lshl_add_u64 v[184:185], v[216:217], 0, s[42:43]
	s_mov_b32 m0, s89
	s_nop 0
	global_load_lds_dwordx4 v[184:185], off
	v_lshl_add_u64 v[184:185], v[218:219], 0, s[42:43]
	s_mov_b32 m0, s90
	s_nop 0
	global_load_lds_dwordx4 v[184:185], off
	s_waitcnt vmcnt(8)
	s_waitcnt lgkmcnt(0)
	s_barrier
	s_setprio 1
	s_waitcnt lgkmcnt(0)
	v_mfma_i32_16x16x64_i8 v[76:79], v[56:59], v[172:175], v[76:79]
	v_mfma_i32_16x16x64_i8 v[72:75], v[64:67], v[172:175], v[72:75]
	v_mfma_i32_16x16x64_i8 v[44:47], v[56:59], v[180:183], v[44:47]
	v_mfma_i32_16x16x64_i8 v[40:43], v[64:67], v[180:183], v[40:43]
	v_mfma_i32_16x16x64_i8 v[28:31], v[56:59], v[200:203], v[28:31]
	v_mfma_i32_16x16x64_i8 v[24:27], v[64:67], v[200:203], v[24:27]
	v_mfma_i32_16x16x64_i8 v[12:15], v[56:59], v[208:211], v[12:15]
	v_mfma_i32_16x16x64_i8 v[8:11], v[64:67], v[208:211], v[8:11]
	v_mfma_i32_16x16x64_i8 v[76:79], v[60:63], v[176:179], v[76:79]
	v_mfma_i32_16x16x64_i8 v[72:75], v[68:71], v[176:179], v[72:75]
	v_mfma_i32_16x16x64_i8 v[44:47], v[60:63], v[190:193], v[44:47]
	v_mfma_i32_16x16x64_i8 v[40:43], v[68:71], v[190:193], v[40:43]
	v_mfma_i32_16x16x64_i8 v[28:31], v[60:63], v[204:207], v[28:31]
	v_mfma_i32_16x16x64_i8 v[24:27], v[68:71], v[204:207], v[24:27]
	v_mfma_i32_16x16x64_i8 v[12:15], v[60:63], v[212:215], v[12:15]
	v_mfma_i32_16x16x64_i8 v[8:11], v[68:71], v[212:215], v[8:11]
	s_setprio 0
	s_setprio 1
	v_mfma_i32_16x16x64_i8 v[48:51], v[156:159], v[172:175], v[48:51]
	v_mfma_i32_16x16x64_i8 v[60:63], v[160:163], v[176:179], v[48:51]
	v_mfma_i32_16x16x64_i8 v[48:51], v[164:167], v[172:175], v[52:55]
	v_mfma_i32_16x16x64_i8 v[36:39], v[156:159], v[180:183], v[36:39]
	v_mfma_i32_16x16x64_i8 v[32:35], v[164:167], v[180:183], v[32:35]
	v_mfma_i32_16x16x64_i8 v[20:23], v[156:159], v[200:203], v[20:23]
	v_mfma_i32_16x16x64_i8 v[16:19], v[164:167], v[200:203], v[16:19]
	v_mfma_i32_16x16x64_i8 v[4:7], v[156:159], v[208:211], v[4:7]
	v_mfma_i32_16x16x64_i8 v[0:3], v[164:167], v[208:211], v[0:3]
	v_mfma_i32_16x16x64_i8 v[56:59], v[168:171], v[176:179], v[48:51]
	v_mfma_i32_16x16x64_i8 v[36:39], v[160:163], v[190:193], v[36:39]
	v_mfma_i32_16x16x64_i8 v[32:35], v[168:171], v[190:193], v[32:35]
	v_mfma_i32_16x16x64_i8 v[20:23], v[160:163], v[204:207], v[20:23]
	v_mfma_i32_16x16x64_i8 v[16:19], v[168:171], v[204:207], v[16:19]
	v_mfma_i32_16x16x64_i8 v[4:7], v[160:163], v[212:215], v[4:7]
	v_mfma_i32_16x16x64_i8 v[0:3], v[168:171], v[212:215], v[0:3]
	s_setprio 0
	s_barrier
	s_add_i32 s65, s65, 2
	s_add_u32 s49, s49, 0x100
	s_addc_u32 s60, s60, 0
	s_add_u32 s46, s46, 0x100
	s_addc_u32 s47, s47, 0
	s_cmp_gt_u32 s65, 29
	s_cbranch_scc0 .LBB0_335
.LBB0_338:
	v_lshl_add_u32 v158, s40, 8, v186
	v_lshl_or_b32 v180, s4, 8, v188
	v_or_b32_e32 v176, 16, v158
	v_or_b32_e32 v172, 32, v158
	v_or_b32_e32 v168, 48, v158
	v_ashrrev_i32_e32 v181, 31, v180
	v_ashrrev_i32_e32 v159, 31, v158
	v_ashrrev_i32_e32 v177, 31, v176
	v_ashrrev_i32_e32 v173, 31, v172
	v_ashrrev_i32_e32 v169, 31, v168
	v_mov_b64_e32 v[64:65], v[222:223]
	v_mov_b64_e32 v[66:67], v[224:225]
	v_mov_b64_e32 v[68:69], v[226:227]
	v_mov_b64_e32 v[70:71], v[228:229]
	v_mov_b64_e32 v[48:49], v[230:231]
	v_mov_b64_e32 v[50:51], v[232:233]
	v_mov_b64_e32 v[52:53], v[242:243]
	v_mov_b64_e32 v[54:55], v[244:245]
	v_cvt_f32_i32_e32 v143, v143
	v_mov_b32_e32 v178, v241
	v_mov_b32_e32 v174, v246
	v_mov_b32_e32 v170, v247
	v_mov_b32_e32 v166, v248
	v_mov_b32_e32 v164, v249
	v_mov_b32_e32 v162, v250
	v_mov_b32_e32 v160, v251
	v_mov_b32_e32 v156, v255
	v_cvt_f32_i32_e32 v142, v142
	v_cvt_f32_i32_e32 v139, v139
	v_cvt_f32_i32_e32 v138, v138
	v_cvt_f32_i32_e32 v145, v145
	v_cvt_f32_i32_e32 v144, v144
	v_cvt_f32_i32_e32 v141, v141
	v_cvt_f32_i32_e32 v140, v140
	s_cmp_gt_i32 s4, 19
	s_cselect_b64 s[46:47], -1, 0
	s_cmp_lt_i32 s4, 20
	s_mov_b64 s[54:55], -1
	s_cselect_b64 s[40:41], -1, 0
	s_and_b64 vcc, exec, s[46:47]
	v_pk_mul_f32 v[142:143], v[178:179], v[142:143] op_sel_hi:[0,1]
	v_pk_mul_f32 v[138:139], v[178:179], v[138:139] op_sel_hi:[0,1]
	v_pk_mul_f32 v[144:145], v[178:179], v[144:145] op_sel_hi:[0,1]
	v_pk_mul_f32 v[140:141], v[178:179], v[140:141] op_sel_hi:[0,1]
	v_pk_mul_f32 v[182:183], v[68:69], v[142:143]
	v_pk_mul_f32 v[142:143], v[64:65], v[138:139]
	v_pk_mul_f32 v[184:185], v[70:71], v[144:145]
	v_pk_mul_f32 v[144:145], v[66:67], v[140:141]
	s_cbranch_vccnz .LBB0_340
	s_mov_b64 s[54:55], 0

; __device__ __forceinline__ unsigned cvt_pk_bf16(float lo, float hi) { const f32x2_t_ v = {lo, hi}; return __builtin_bit_cast(unsigned, __builtin_convertvector(v, bf16x2_t_)); }
; #define PG8_BAR __builtin_amdgcn_s_barrier()
;     __device__ __forceinline__ void operator()(const i32x4 (&acc)[2][2][4][2], const Unit& u, int wr, int wc, int fr, int fq) const {
;     ...
;                     u32x4 w; w.x = cvt_pk_bf16(v0[0], v0[1]); w.y = cvt_pk_bf16(v0[2], v0[3]); w.z = cvt_pk_bf16(v1[0], v1[1]); w.w = cvt_pk_bf16(v1[2], v1[3]);
;                     *(u32x4*)(rowp + bj * HALF) = w; } }
; template <class Epi, class Sched, bool ALIGN_EPI = false, bool SP2 = false, bool I8 = false>
; __device__ __forceinline__ void gemm_phase(PG8_LAS unsigned char* lds, const Gemm g, const Sched& S, const Epi& E, const int tid) {
;     ...
;         if constexpr (ALIGN_EPI) { if (wr == 0) PG8_BAR; }
;         if constexpr (!Epi::AFTER_DRAIN) { E(acc, cur, wr, wc, fr, fq); S.done(cur); }
;         if (!has_next) break;
; #pragma unroll
;         for (int a = 0; a < 2; ++a)
; #pragma unroll
;             for (int b = 0; b < 2; ++b)
; #pragma unroll
;                 for (int m = 0; m < 4; ++m)
; #pragma unroll
;                     for (int n = 0; n < 2; ++n) acc[a][b][m][n] = AccT<I8>::zero();
;         cur = nxt; cA = nA; cB = nB; ++ui;
;         if constexpr (ALIGN_EPI) { if (wr == 1) PG8_BAR; }
.LBB0_402:
	v_cvt_pk_bf16_f32 v0, v0, v1
	v_cvt_pk_bf16_f32 v1, v4, v5
	v_cvt_pk_bf16_f32 v2, v2, v3
	v_cvt_pk_bf16_f32 v3, v6, v7
	s_and_b64 vcc, exec, s[26:27]
	s_cbranch_vccz .Lepi_nb
	s_barrier
.Lepi_nb:
	s_andn2_b64 vcc, exec, s[36:37]
	s_mov_b64 s[4:5], -1
	global_store_dwordx4 v[8:9], v[0:3], off offset:256
	s_cbranch_vccnz .LBB0_304
	s_andn2_b64 vcc, exec, s[10:11]
	s_cbranch_vccnz .LBB0_303
	s_barrier
	s_branch .LBB0_303
